# NA items of one (batch,head) share an XCD; pool item window rows loaded with all five loads in flight
# baseline (speedup 1.0000x reference)
; DI void pool_item(const Params& p, int l, int token0, char* lds) {
;     ...
;   for (int e = tid; e < 80 * 32; e += NTHREADS) {
;     const int row = e >> 5, ch = e & 31;
;     const int s = s0 - 8 + row;
;     u32x4 v = {0u, 0u, 0u, 0u};
;     if (s >= 0 && s < L) v = *(const u32x4*)(p.P + (size_t)(seqbase + s) * INW + 1280 + ch * 8);
;     *(u32x4*)(zt + row * 512 + ch * 16) = v;
;   }
.LBB0_86:
.LBB0_87:
	v_ashrrev_i32_e32 v10, 5, v7
	s_nop 0
	v_add_u32_e32 v11, s9, v10
	v_cmp_gt_u32_e32 vcc, s0, v11
	v_mov_b32_e32 v108, 0
	v_mov_b32_e32 v109, 0
	v_mov_b32_e32 v110, 0
	v_mov_b32_e32 v111, 0
	s_and_saveexec_b64 s[6:7], vcc
	v_add_u32_e32 v106, s8, v11
	v_mad_u64_u32 v[106:107], s[10:11], v106, s90, v[8:9]
	global_load_dwordx4 v[108:111], v[106:107], off offset:2560
	s_or_b64 exec, exec, s[6:7]
	v_ashrrev_i32_e32 v10, 5, v7
	v_add_u32_e32 v10, 16, v10
	v_add_u32_e32 v11, s9, v10
	v_cmp_gt_u32_e32 vcc, s0, v11
	v_mov_b32_e32 v112, 0
	v_mov_b32_e32 v113, 0
	v_mov_b32_e32 v114, 0
	v_mov_b32_e32 v115, 0
	s_and_saveexec_b64 s[6:7], vcc
	v_add_u32_e32 v106, s8, v11
	v_mad_u64_u32 v[106:107], s[10:11], v106, s90, v[8:9]
	global_load_dwordx4 v[112:115], v[106:107], off offset:2560
	s_or_b64 exec, exec, s[6:7]
	v_ashrrev_i32_e32 v10, 5, v7
	v_add_u32_e32 v10, 32, v10
	v_add_u32_e32 v11, s9, v10
	v_cmp_gt_u32_e32 vcc, s0, v11
	v_mov_b32_e32 v116, 0
	v_mov_b32_e32 v117, 0
	v_mov_b32_e32 v118, 0
	v_mov_b32_e32 v119, 0
	s_and_saveexec_b64 s[6:7], vcc
	v_add_u32_e32 v106, s8, v11
	v_mad_u64_u32 v[106:107], s[10:11], v106, s90, v[8:9]
	global_load_dwordx4 v[116:119], v[106:107], off offset:2560
	s_or_b64 exec, exec, s[6:7]
	v_ashrrev_i32_e32 v10, 5, v7
	v_add_u32_e32 v10, 48, v10
	v_add_u32_e32 v11, s9, v10
	v_cmp_gt_u32_e32 vcc, s0, v11
	v_mov_b32_e32 v120, 0
	v_mov_b32_e32 v121, 0
	v_mov_b32_e32 v122, 0
	v_mov_b32_e32 v123, 0
	s_and_saveexec_b64 s[6:7], vcc
	v_add_u32_e32 v106, s8, v11
	v_mad_u64_u32 v[106:107], s[10:11], v106, s90, v[8:9]
	global_load_dwordx4 v[120:123], v[106:107], off offset:2560
	s_or_b64 exec, exec, s[6:7]
	v_ashrrev_i32_e32 v10, 5, v7
	v_add_u32_e32 v10, 64, v10
	v_add_u32_e32 v11, s9, v10
	v_cmp_gt_u32_e32 vcc, s0, v11
	v_mov_b32_e32 v124, 0
	v_mov_b32_e32 v125, 0
	v_mov_b32_e32 v126, 0
	v_mov_b32_e32 v127, 0
	s_and_saveexec_b64 s[6:7], vcc
	v_add_u32_e32 v106, s8, v11
	v_mad_u64_u32 v[106:107], s[10:11], v106, s90, v[8:9]
	global_load_dwordx4 v[124:127], v[106:107], off offset:2560
	s_or_b64 exec, exec, s[6:7]
	s_waitcnt vmcnt(0)
	v_ashrrev_i32_e32 v10, 5, v7
	v_lshl_or_b32 v10, v10, 9, v6
	ds_write_b128 v10, v[108:111]
	v_ashrrev_i32_e32 v10, 5, v7
	v_add_u32_e32 v10, 16, v10
	v_lshl_or_b32 v10, v10, 9, v6
	ds_write_b128 v10, v[112:115]
	v_ashrrev_i32_e32 v10, 5, v7
	v_add_u32_e32 v10, 32, v10
	v_lshl_or_b32 v10, v10, 9, v6
	ds_write_b128 v10, v[116:119]
	v_ashrrev_i32_e32 v10, 5, v7
	v_add_u32_e32 v10, 48, v10
	v_lshl_or_b32 v10, v10, 9, v6
	ds_write_b128 v10, v[120:123]
	v_ashrrev_i32_e32 v10, 5, v7
	v_add_u32_e32 v10, 64, v10
	v_lshl_or_b32 v10, v10, 9, v6
	ds_write_b128 v10, v[124:127]

; DI void phaseB(const Params& p, int l, char* lds) {
;     ...
;     } else if (idx < nG + nN) {
;       idx -= nG;
;       b = idx >> 5; const int rem = idx & 31; head = rem >> 3; kvh = head; rq = rem & 7;
;       rlo = clampi(4 * rq - 4, 0, 24);
;       const int rhi = clampi(4 * rq + 3 - 4, 0, 24);
;       nt1 = rhi + 8 - rlo; qrow = b * SEQ + rq * 256; k1row = b * SEQ + rlo * 64; vk1 = rlo * 64; isN = true; na = true;
.LBB0_105:
	s_mov_b32 s24, 0
	s_mov_b64 s[8:9], 0
	s_andn2_b64 vcc, exec, s[2:3]
	s_mov_b64 s[6:7], 0
	s_mov_b32 s89, 0
	s_mov_b32 s90, 0
	s_mov_b32 s79, 0
	s_mov_b32 s2, 0
	s_cbranch_vccnz .LBB0_107
	s_add_i32 s6, s83, 0xfffffc00
	s_bfe_u32 s7, s6, 0x30003
	s_and_b32 s5, s6, 3
	s_lshl_b32 s5, s5, 3
	s_or_b32 s7, s7, s5
	s_bfe_u32 s5, s6, 0x10002
	s_lshr_b32 s10, s6, 6
	s_lshl_b32 s10, s10, 1
	s_add_i32 s5, s5, s10
	s_lshl_b32 s5, s5, 5
	s_or_b32 s7, s7, s5
	s_addk_i32 s7, 0x400
	s_and_b32 s2, s7, 7
	s_lshl_b32 s24, s2, 2
	s_add_i32 s4, s24, -1
	s_add_i32 s0, s7, 0xfffffc00
	s_add_i32 s3, s24, -4
	s_min_u32 s4, s4, 24
	s_lshr_b32 s0, s0, 5
	s_bfe_u32 s25, s7, 0x20003
	s_min_u32 s3, s3, 24
	s_add_i32 s4, s4, 8
	s_cmp_eq_u32 s2, 0
	s_cselect_b32 s89, 0, s3
	s_cselect_b32 s3, 8, s4
	s_sub_i32 s79, s3, s89
	s_lshl_b32 s3, s0, 11
	s_lshl_b32 s2, s2, 8
	s_lshl_b32 s90, s89, 6
	s_or_b32 s11, s3, s2
	s_or_b32 s2, s90, s3
	s_mov_b64 s[6:7], -1
	s_mov_b64 s[4:5], -1
	s_mov_b32 s10, s25

; template <bool NA, bool TRACK>
; DI void attn_item(char* lds, const bf16_t* P, bf16_t* Y, const bf16_t* vt, int rp, int q_off, int k1_off, int nt1,
;                   int vk1, int k2_off, int nt2, int vk2, int g_off, int y_off, int rlo, const float* rpb) {
;     ...
;   if (NA) {
;     rw = rp * 4 + (w >> 1);
;     r0w = clampi(rw - 4, 0, 24);
;     cq = (w & 1) * 32 + r;
;     c0 = clampi(cq - 8, 0, 48);
;     for (int e = tid; e < 15 * 128; e += NTHREADS) {
;       const int dr = e >> 7, dc = (e & 127) - 48;
;       tab[e] = (dc >= 0 && dc < 31) ? rpb[dr * 31 + dc] * LOG2E : 0.f;
;     }
;   }
;   bf16x8 qf[4];
; #pragma unroll
;   for (int ks = 0; ks < 4; ++ks) qf[ks] = *(const bf16x8*)(qp + (size_t)(w * 32 + r) * INW + ks * 16 + h * 8);
;   u32x2 gate[2][4];
; #pragma unroll
;   for (int dm = 0; dm < 2; ++dm)
; #pragma unroll
;     for (int g = 0; g < 4; ++g)
;       gate[dm][g] = *(const u32x2*)(P + g_off + (size_t)(w * 32 + r) * INW + dm * 32 + 8 * g + 4 * h);
;     ...
;   ATT_LOAD(0);
.LBB0_185:
	v_readlane_b32 s2, v255, 10
	v_readlane_b32 s3, v255, 11
	s_nop 3
	s_cmp_eq_u64 s[2:3], 0
	s_cbranch_scc1 .Lna_orig
	v_readlane_b32 s0, v255, 12
	v_readlane_b32 s46, v254, 37
	v_readlane_b32 s47, v254, 38
	s_nop 3
	s_add_i32 s0, s25, s0
	s_mul_i32 s0, s0, 0x744
	s_add_u32 s46, s46, s0
	s_addc_u32 s47, s47, 0
	v_and_b32_e32 v0, 0x7f, v251
	v_subrev_u32_e32 v0, 48, v0
	v_cmp_gt_u32_e32 vcc, 31, v0
	v_med3_i32 v0, v0, 0, 30
	v_lshrrev_b32_e32 v162, 7, v251
	v_mul_u32_u24_e32 v163, 31, v162
	v_add_lshl_u32 v163, v163, v0, 2
	global_load_dword v195, v163, s[46:47]
	global_load_dword v196, v163, s[46:47] offset:496
	global_load_dword v197, v163, s[46:47] offset:992
	v_min_u32_e32 v162, 2, v162
	v_mul_u32_u24_e32 v162, 31, v162
	v_add_lshl_u32 v162, v162, v0, 2
	global_load_dword v198, v162, s[46:47] offset:1488
	v_readlane_b32 s44, v254, 49
	v_readlane_b32 s45, v254, 50
	s_ashr_i32 s13, s12, 31
	s_ashr_i32 s11, s10, 31
	s_mov_b32 s34, s26
	s_ashr_i32 s35, s26, 31
	s_lshl_b64 s[34:35], s[34:35], 1
	s_add_u32 s34, s34, s44
	s_addc_u32 s35, s35, s45
	s_mov_b32 s36, s27
	s_ashr_i32 s37, s27, 31
	s_lshl_b64 s[36:37], s[36:37], 1
	s_add_u32 s36, s36, s44
	s_addc_u32 s37, s37, s45
	s_lshl_b64 s[4:5], s[12:13], 1
	s_add_u32 s4, s4, s44
	s_addc_u32 s5, s5, s45
	s_lshl_b64 s[6:7], s[10:11], 1
	s_add_u32 s6, s6, s44
	s_addc_u32 s7, s7, s45
	s_add_i32 s30, s79, 4
	s_add_i32 s19, s30, 3
	s_lshr_b32 s19, s19, 2
	s_mov_b32 s18, 0
	v_bfe_u32 v183, v251, 5, 1
	v_ashrrev_i32_e32 v0, 1, v251
	s_movk_i32 s0, 0xffe0
	v_bfi_b32 v182, s0, v0, v251
	v_lshlrev_b32_e32 v174, 3, v183
	v_mov_b32_e32 v172, s28
	v_mul_u32_u24_e32 v0, 0x1600, v182
	v_lshl_add_u32 v204, v183, 4, v0
	v_lshl_add_u32 v205, v183, 3, v0
	v_lshrrev_b32_e32 v0, 3, v251
	v_and_b32_e32 v162, 7, v251
	v_mul_u32_u24_e32 v200, 0x1600, v0
	v_lshl_add_u32 v200, v162, 4, v200
	v_mul_u32_u24_e32 v201, 0x1200, v0
	v_lshl_add_u32 v201, v162, 4, v201
	global_load_dwordx4 v[66:69], v204, s[34:35]
	global_load_dwordx4 v[70:73], v204, s[34:35] offset:32
	global_load_dwordx4 v[74:77], v204, s[34:35] offset:64
	global_load_dwordx4 v[78:81], v204, s[34:35] offset:96
	s_mov_b32 s31, 0
	s_cmp_lt_i32 s31, s79
	s_cselect_b32 s21, 0, s79
	s_cselect_b32 s22, s4, s6
	s_cselect_b32 s23, s5, s7
	s_cselect_b32 s29, s90, 0x800
	s_sub_i32 s20, s31, s21
	s_mul_i32 s21, s20, 0x58000
	s_add_u32 s14, s22, s21
	s_addc_u32 s15, s23, 0
	s_lshl_b32 s20, s20, 6
	s_add_i32 s20, s20, s29
	s_lshl_b32 s20, s20, 1
	s_add_u32 s16, s8, s20
	s_addc_u32 s17, s9, 0
	global_load_dwordx4 v[130:133], v200, s[14:15]
	global_load_dwordx4 v[134:137], v201, s[16:17]
	s_mov_b32 s31, 1
	s_cmp_lt_i32 s31, s79
	s_cselect_b32 s21, 0, s79
	s_cselect_b32 s22, s4, s6
	s_cselect_b32 s23, s5, s7
	s_cselect_b32 s29, s90, 0x800
	s_sub_i32 s20, s31, s21
	s_mul_i32 s21, s20, 0x58000
	s_add_u32 s14, s22, s21
	s_addc_u32 s15, s23, 0
	s_lshl_b32 s20, s20, 6
	s_add_i32 s20, s20, s29
	s_lshl_b32 s20, s20, 1
	s_add_u32 s16, s8, s20
	s_addc_u32 s17, s9, 0
	global_load_dwordx4 v[138:141], v200, s[14:15]
	global_load_dwordx4 v[142:145], v201, s[16:17]
	s_mov_b32 s31, 2
	s_cmp_lt_i32 s31, s79
	s_cselect_b32 s21, 0, s79
	s_cselect_b32 s22, s4, s6
	s_cselect_b32 s23, s5, s7
	s_cselect_b32 s29, s90, 0x800
	s_sub_i32 s20, s31, s21
	s_mul_i32 s21, s20, 0x58000
	s_add_u32 s14, s22, s21
	s_addc_u32 s15, s23, 0
	s_lshl_b32 s20, s20, 6
	s_add_i32 s20, s20, s29
	s_lshl_b32 s20, s20, 1
	s_add_u32 s16, s8, s20
	s_addc_u32 s17, s9, 0
	global_load_dwordx4 v[146:149], v200, s[14:15]
	global_load_dwordx4 v[150:153], v201, s[16:17]
	s_mov_b32 s31, 3
	s_cmp_lt_i32 s31, s79
	s_cselect_b32 s21, 0, s79
	s_cselect_b32 s22, s4, s6
	s_cselect_b32 s23, s5, s7
	s_cselect_b32 s29, s90, 0x800
	s_sub_i32 s20, s31, s21
	s_mul_i32 s21, s20, 0x58000
	s_add_u32 s14, s22, s21
	s_addc_u32 s15, s23, 0
	s_lshl_b32 s20, s20, 6
	s_add_i32 s20, s20, s29
	s_lshl_b32 s20, s20, 1
	s_add_u32 s16, s8, s20
	s_addc_u32 s17, s9, 0
	global_load_dwordx4 v[154:157], v200, s[14:15]
	global_load_dwordx4 v[158:161], v201, s[16:17]
	global_load_dwordx2 v[184:185], v205, s[36:37]
	global_load_dwordx2 v[180:181], v205, s[36:37] offset:16
	global_load_dwordx2 v[178:179], v205, s[36:37] offset:32
	global_load_dwordx2 v[176:177], v205, s[36:37] offset:48
	global_load_dwordx2 v[170:171], v205, s[36:37] offset:64
	global_load_dwordx2 v[168:169], v205, s[36:37] offset:80
	global_load_dwordx2 v[166:167], v205, s[36:37] offset:96
	global_load_dwordx2 v[164:165], v205, s[36:37] offset:112
	s_waitcnt vmcnt(20)
; DI int get_tid() { int t = threadIdx.x; asm volatile("" : "+v"(t)); return t; }
; template <bool NA, bool TRACK>
; DI void attn_item(char* lds, const bf16_t* P, bf16_t* Y, const bf16_t* vt, int rp, int q_off, int k1_off, int nt1,
;                   int vk1, int k2_off, int nt2, int vk2, int g_off, int y_off, int rlo, const float* rpb) {
;     ...
;   const int tid = get_tid(), lane = tid & 63, w = tid >> 6, r = lane & 31, h = lane >> 5;
;   const int lr = tid >> 3, lc = tid & 7;
;   const int nt = nt1 + nt2;
;   const int woff = lr * 128 + ((lc ^ ((lr >> 1) & 7)) << 4);
;   const int swz = (r >> 1) & 7;
;   float* tab = (float*)(lds + 131072);
;   int rw = 0, r0w = 0, cq = 0, c0 = 0;
;   if (NA) {
;     rw = rp * 4 + (w >> 1);
;     r0w = clampi(rw - 4, 0, 24);
;     cq = (w & 1) * 32 + r;
;     c0 = clampi(cq - 8, 0, 48);
;     for (int e = tid; e < 15 * 128; e += NTHREADS) {
;       const int dr = e >> 7, dc = (e & 127) - 48;
;       tab[e] = (dc >= 0 && dc < 31) ? rpb[dr * 31 + dc] * LOG2E : 0.f;
;     }
;   }
;   bf16x8 qf[4];
; #pragma unroll
;   for (int ks = 0; ks < 4; ++ks) qf[ks] = *(const bf16x8*)(qp + (size_t)(w * 32 + r) * INW + ks * 16 + h * 8);
;   u32x2 gate[2][4];
; #pragma unroll
;   for (int dm = 0; dm < 2; ++dm)
; #pragma unroll
;     for (int g = 0; g < 4; ++g)
;       gate[dm][g] = *(const u32x2*)(P + g_off + (size_t)(w * 32 + r) * INW + dm * 32 + 8 * g + 4 * h);
; #pragma unroll
;   for (int ks = 0; ks < 4; ++ks) asm volatile("" : "+v"(qf[ks]));
; #pragma unroll
;   for (int dm = 0; dm < 2; ++dm)
; #pragma unroll
;     for (int g = 0; g < 4; ++g) asm volatile("" : "+v"(gate[dm][g]));
;   f32x16 o[2];
;   o[0] = zero16(); o[1] = zero16();
;   f32x16 negm;
; #pragma unroll
;   for (int i = 0; i < 16; ++i) negm[i] = 0.f;
;   float l_run = 0.f;
	v_lshlrev_b32_e32 v163, 2, v251
	v_add_u32_e32 v163, 0x20000, v163
	v_mov_b32_e32 v203, 0
	v_mul_f32_e32 v195, 0x3fb8aa3b, v195
	v_cndmask_b32_e32 v195, 0, v195, vcc
	v_max_f32_e64 v203, v203, |v195|
	v_mul_f32_e32 v196, 0x3fb8aa3b, v196
	v_cndmask_b32_e32 v196, 0, v196, vcc
	v_max_f32_e64 v203, v203, |v196|
	v_mul_f32_e32 v197, 0x3fb8aa3b, v197
	v_cndmask_b32_e32 v197, 0, v197, vcc
	v_max_f32_e64 v203, v203, |v197|
	v_mul_f32_e32 v198, 0x3fb8aa3b, v198
	v_cndmask_b32_e32 v198, 0, v198, vcc
	v_max_f32_e64 v203, v203, |v198|
	ds_write_b32 v163, v195
	ds_write_b32 v163, v196 offset:2048
	ds_write_b32 v163, v197 offset:4096
	s_movk_i32 s0, 0x180
	v_cmp_gt_u32_e64 s[2:3], s0, v251
	s_nop 3
	s_and_saveexec_b64 s[14:15], s[2:3]
	ds_write_b32 v163, v198 offset:6144
	s_mov_b64 exec, s[14:15]
	s_mov_b32 s0, 0x41c00000
	v_cmp_lt_f32_e32 vcc, s0, v203
	s_nop 4
	s_cmp_lg_u64 vcc, 0
	s_cselect_b32 s0, 1, 0
	v_mov_b32_e32 v203, s0
	v_lshrrev_b32_e32 v163, 6, v251
	v_lshlrev_b32_e32 v163, 2, v163
	v_add_u32_e32 v163, 0x1ffe0, v163
	ds_write_b32 v163, v203
	v_lshlrev_b32_e32 v162, 4, v251
	v_xor_b32_e32 v162, v162, v251
	v_and_b32_e32 v162, 0x70, v162
	v_lshl_or_b32 v199, v0, 7, v162
	v_and_b32_e32 v0, 31, v251
	v_lshlrev_b32_e32 v0, 7, v0
	v_bfe_u32 v162, v251, 1, 3
	v_xor_b32_e32 v162, v162, v183
	v_lshl_or_b32 v191, v162, 4, v0
	v_xor_b32_e32 v163, 2, v162
	v_lshl_or_b32 v192, v163, 4, v0
	v_xor_b32_e32 v163, 4, v162
	v_lshl_or_b32 v193, v163, 4, v0
	v_xor_b32_e32 v163, 6, v162
	v_lshl_or_b32 v194, v163, 4, v0
	v_mov_b32_e32 v2, 0
	v_mov_b32_e32 v3, 0
	v_mov_b32_e32 v4, 0
	v_mov_b32_e32 v5, 0
	v_mov_b32_e32 v6, 0
	v_mov_b32_e32 v7, 0
	v_mov_b32_e32 v8, 0
	v_mov_b32_e32 v9, 0
	v_mov_b32_e32 v10, 0
	v_mov_b32_e32 v11, 0
	v_mov_b32_e32 v12, 0
	v_mov_b32_e32 v13, 0
	v_mov_b32_e32 v14, 0
	v_mov_b32_e32 v15, 0
	v_mov_b32_e32 v16, 0
	v_mov_b32_e32 v17, 0
	v_mov_b32_e32 v18, 0
	v_mov_b32_e32 v19, 0
	v_mov_b32_e32 v20, 0
	v_mov_b32_e32 v21, 0
	v_mov_b32_e32 v22, 0
	v_mov_b32_e32 v23, 0
	v_mov_b32_e32 v24, 0
	v_mov_b32_e32 v25, 0
	v_mov_b32_e32 v26, 0
	v_mov_b32_e32 v27, 0
	v_mov_b32_e32 v28, 0
	v_mov_b32_e32 v29, 0
	v_mov_b32_e32 v30, 0
	v_mov_b32_e32 v31, 0
	v_mov_b32_e32 v32, 0
	v_mov_b32_e32 v33, 0
	v_mov_b32_e32 v186, 0
	v_mov_b32_e32 v187, 0
	v_mov_b32_e32 v188, 0
	v_mov_b32_e32 v189, 0
	v_mov_b32_e32 v114, 0
	v_mov_b32_e32 v115, 0
	v_mov_b32_e32 v116, 0
	v_mov_b32_e32 v117, 0
	v_mov_b32_e32 v118, 0
	v_mov_b32_e32 v119, 0
	v_mov_b32_e32 v120, 0
	v_mov_b32_e32 v121, 0
	v_mov_b32_e32 v122, 0
	v_mov_b32_e32 v123, 0
	v_mov_b32_e32 v124, 0
	v_mov_b32_e32 v125, 0
	v_mov_b32_e32 v126, 0
	v_mov_b32_e32 v127, 0
	v_mov_b32_e32 v128, 0
	v_mov_b32_e32 v129, 0
	v_lshrrev_b32_e32 v0, 6, v251
	s_nop 0
	v_readfirstlane_b32 s39, v0
	s_nop 3
	s_lshr_b32 s38, s39, 1
	s_add_i32 s38, s38, s24
	s_sub_i32 s40, s89, s38
	s_add_i32 s40, s40, 7
	s_sub_i32 s38, s38, 4
	s_max_i32 s38, s38, 0
	s_min_i32 s38, s38, 24
	s_sub_i32 s38, s38, s89
	s_and_b32 s39, s39, 1
	v_and_b32_e32 v0, 31, v251
	s_lshl_b32 s0, s39, 5
	v_add_u32_e32 v0, s0, v0
	v_subrev_u32_e32 v162, 8, v0
	v_med3_i32 v162, v162, 0, 48
	v_lshlrev_b32_e32 v163, 2, v183
	v_sub_u32_e32 v162, v163, v162
	v_sub_u32_e32 v0, v163, v0
	v_add_u32_e32 v0, 63, v0
	v_lshlrev_b32_e32 v202, 2, v0
	v_add_u32_e32 v202, 0x20000, v202
	s_cmp_eq_u32 s39, 0
	s_cbranch_scc0 .Lna_mask1
	v_add_u32_e32 v163, 0, v162
	v_cmp_gt_u32_e32 vcc, 16, v163
	s_nop 1
	v_cndmask_b32_e32 v206, v249, v250, vcc
	v_add_u32_e32 v163, 1, v162
	v_cmp_gt_u32_e32 vcc, 16, v163
	s_nop 1
	v_cndmask_b32_e32 v207, v249, v250, vcc
	v_add_u32_e32 v163, 2, v162
	v_cmp_gt_u32_e32 vcc, 16, v163
	s_nop 1
	v_cndmask_b32_e32 v208, v249, v250, vcc
	v_add_u32_e32 v163, 3, v162
	v_cmp_gt_u32_e32 vcc, 16, v163
	s_nop 1
	v_cndmask_b32_e32 v209, v249, v250, vcc
	v_add_u32_e32 v163, 8, v162
	v_cmp_gt_u32_e32 vcc, 16, v163
	s_nop 1
	v_cndmask_b32_e32 v210, v249, v250, vcc
	v_add_u32_e32 v163, 9, v162
	v_cmp_gt_u32_e32 vcc, 16, v163
	s_nop 1
	v_cndmask_b32_e32 v211, v249, v250, vcc
	v_add_u32_e32 v163, 10, v162
	v_cmp_gt_u32_e32 vcc, 16, v163
	s_nop 1
	v_cndmask_b32_e32 v212, v249, v250, vcc
	v_add_u32_e32 v163, 11, v162
	v_cmp_gt_u32_e32 vcc, 16, v163
	s_nop 1
	v_cndmask_b32_e32 v213, v249, v250, vcc
	v_add_u32_e32 v163, 16, v162
	v_cmp_gt_u32_e32 vcc, 16, v163
	s_nop 1
	v_cndmask_b32_e32 v214, v249, v250, vcc
	v_add_u32_e32 v163, 17, v162
	v_cmp_gt_u32_e32 vcc, 16, v163
	s_nop 1
	v_cndmask_b32_e32 v215, v249, v250, vcc
	v_add_u32_e32 v163, 18, v162
	v_cmp_gt_u32_e32 vcc, 16, v163
	s_nop 1
	v_cndmask_b32_e32 v216, v249, v250, vcc
	v_add_u32_e32 v163, 19, v162
	v_cmp_gt_u32_e32 vcc, 16, v163
	s_nop 1
	v_cndmask_b32_e32 v217, v249, v250, vcc
	v_add_u32_e32 v163, 24, v162
	v_cmp_gt_u32_e32 vcc, 16, v163
	s_nop 1
	v_cndmask_b32_e32 v218, v249, v250, vcc
	v_add_u32_e32 v163, 25, v162
	v_cmp_gt_u32_e32 vcc, 16, v163
	s_nop 1
	v_cndmask_b32_e32 v219, v249, v250, vcc
	v_add_u32_e32 v163, 26, v162
	v_cmp_gt_u32_e32 vcc, 16, v163
	s_nop 1
	v_cndmask_b32_e32 v220, v249, v250, vcc
	v_add_u32_e32 v163, 27, v162
	v_cmp_gt_u32_e32 vcc, 16, v163
	s_nop 1
	v_cndmask_b32_e32 v221, v249, v250, vcc
	v_add_u32_e32 v163, 32, v162
	v_cmp_gt_u32_e32 vcc, 16, v163
	s_nop 1
	v_cndmask_b32_e32 v222, v249, v250, vcc
	v_add_u32_e32 v163, 33, v162
	v_cmp_gt_u32_e32 vcc, 16, v163
	s_nop 1
	v_cndmask_b32_e32 v223, v249, v250, vcc
	v_add_u32_e32 v163, 34, v162
	v_cmp_gt_u32_e32 vcc, 16, v163
	s_nop 1
	v_cndmask_b32_e32 v224, v249, v250, vcc
	v_add_u32_e32 v163, 35, v162
	v_cmp_gt_u32_e32 vcc, 16, v163
	s_nop 1
	v_cndmask_b32_e32 v225, v249, v250, vcc
	s_branch .Lna_maskd
